# P9 in-place residual epilogue batched like P5, plus odd workgroups start P9 ~12us later (de-lockstep HBM bursts)
# baseline (speedup 1.0000x reference)
; template <class Epi, class Sched, bool ALIGN_EPI = false, bool SP2 = false>
; __device__ __forceinline__ void gemm_phase(PG8_LAS unsigned char* lds, const Gemm g, const Sched& S, const Epi& E) {
;     int tid_ = threadIdx.x; asm volatile("" : "+v"(tid_)); const int tid = tid_, wid = __builtin_amdgcn_readfirstlane(tid >> 6), lane = tid & 63, wr = wid >> 2, wc = wid & 3, fr = lane & 15, fq = lane >> 4;
;     const int K = g.K, nt = K / BK;
;     unsigned voffA[2], voffB[2];
; #pragma unroll
;     for (int i = 0; i < 2; ++i) { int R, C; stage_rc(tid * 16 + i * 8192, R, C); const int Rb = Epi::PERM ? ((R & ~31) + perm32(R & 31)) : R;
;         voffA[i] = (unsigned)(R * g.lda + C) * 2u; voffB[i] = (unsigned)(Rb * K + C) * 2u; }
;     const size_t kstep = (size_t)(BK * 2);
;     const size_t hstepA = (size_t)HALF * g.lda * 2, hstepB = (size_t)HALF * K * 2;
;     const size_t tstepA = 2 * hstepA, tstepB = 2 * hstepB;
;     const unsigned ldsw = (unsigned)wid * 1024u;
;     const int aoff = lds_byte(wr * 64 + fr, fq * 8), boff = lds_byte(wc * 32 + fr, fq * 8);
;     ...
;     Unit cur, nxt; int ui = 0;
;     if (!S.next(0, cur)) return;
;     f32x4 acc[2][2][4][2];
; #pragma unroll
;     for (int a = 0; a < 2; ++a)
; #pragma unroll
;         for (int b = 0; b < 2; ++b)
; #pragma unroll
;             for (int m = 0; m < 4; ++m)
; #pragma unroll
;                 for (int n = 0; n < 2; ++n) acc[a][b][m][n] = (f32x4){0.f, 0.f, 0.f, 0.f};
;     bf16x8 At[4][2], B0[2][2], B1[2][2];
;     const char* cA = (const char*)g.A + (size_t)cur.pm * tstepA; const char* cB = (const char*)g.Bt + (size_t)cur.pn * tstepB;
;     S.a_ready(cur);
;     if constexpr (SP2) {
;         PG8_STAGE(PG8_SB(0, 0), cB, voffB); PG8_STAGE(PG8_SB(0, 1), cB + hstepB, voffB); PG8_STAGE(PG8_SA(0, 0), cA, voffA); PG8_STAGE(PG8_SA(0, 1), cA + hstepA, voffA);
;         if (wr == 1) PG8_BAR;
;         PG8_WAIT_V(2); PG8_BAR;
;         PG8_STAGE(PG8_SB(1, 0), cB + kstep, voffB); PG8_STAGE(PG8_SA(1, 0), cA + kstep, voffA); PG8_STAGE(PG8_SB(1, 1), cB + hstepB + kstep, voffB);
;         PG8_WAIT_V(6); PG8_BAR;
; __global__ void __launch_bounds__(512, 2) fwd_megakernel(Params p_unused) {
;     ...
;     pg8::StaticOrder S; S.init(MTOK, DM, G, bx);
;     pg8::Gemm g{U, WDN, MTOK, DM, FF, FF}; pg8::EpiRes E{p.out, p.out, mod + 10240};
;     pg8::gemm_phase<pg8::EpiRes, pg8::StaticOrder, true, true>(glds, g, S, E);
.LBB0_877:
	s_or_b64 exec, exec, s[4:5]
	s_mov_b64 s[4:5], s[86:87]
	s_waitcnt lgkmcnt(0)
	v_mov_b32_e32 v0, v194
	v_mov_b32_e32 v8, v194
	s_barrier
	s_bitcmp1_b32 s96, 0
	s_cbranch_scc0 .Lskew_p9_done
	s_sleep 127
	s_sleep 127
	s_sleep 127
.Lskew_p9_done:
	s_and_b64 vcc, exec, s[14:15]
	v_readfirstlane_b32 s6, v8
	s_cbranch_vccz .LBB0_901
	v_lshlrev_b32_e32 v0, 4, v8
	v_add_u32_e32 v1, 0x2000, v0
	s_load_dwordx4 s[8:11], s[4:5], 0xc0
	v_ashrrev_i32_e32 v2, 31, v1
	v_lshrrev_b32_e32 v2, 22, v2
	v_add_u32_e32 v2, v1, v2
	v_ashrrev_i32_e32 v9, 10, v2
	v_mul_i32_i24_e32 v2, 0x400, v9
	s_waitcnt lgkmcnt(0)
	s_add_u32 s0, s10, 0x9b00000
	v_sub_u32_e32 v1, v1, v2
	s_addc_u32 s1, s11, 0
	v_lshrrev_b32_e32 v2, 4, v1
	s_add_u32 s2, s10, 0x2e00000
	v_bitop3_b32 v1, v2, v1, 32 bitop3:0x6c
	s_addc_u32 s3, s11, 0
	s_ashr_i32 s7, s6, 6
	v_ashrrev_i32_e32 v2, 31, v1
	s_ashr_i32 s5, s6, 8
	s_lshl_b32 s33, s7, 10
	v_lshrrev_b32_e32 v2, 26, v2
	v_add_u32_e32 v2, v1, v2
	s_and_b64 s[12:13], s[12:13], exec
	v_ashrrev_i32_e32 v10, 6, v2
	v_and_b32_e32 v2, 0xc0, v2
	s_cselect_b32 s12, s59, s58
	v_sub_u32_e32 v1, v1, v2
	v_mov_b32_e32 v2, 1
	s_add_i32 s12, s12, s57
	v_ashrrev_i16_sdwa v1, v2, sext(v1) dst_sel:DWORD dst_unused:UNUSED_PAD src0_sel:DWORD src1_sel:BYTE_0
	s_ashr_i32 s13, s12, 31
	v_lshlrev_b32_e32 v3, 3, v9
	v_bfe_i32 v12, v1, 0, 16
	v_bfe_i32 v1, v8, 27, 1
	s_lshr_b32 s13, s13, 27
	v_and_b32_e32 v3, 0x7ffff0, v3
	v_lshrrev_b32_e32 v1, 22, v1
	s_add_i32 s13, s12, s13
	v_add_u32_e32 v3, v10, v3
	s_movk_i32 s4, 0x1600
	v_lshlrev_b32_e32 v4, 5, v9
	v_add_u32_e32 v1, v0, v1
	s_ashr_i32 s14, s13, 5
	s_and_b32 s13, s13, 0xffe0
	v_mul_lo_u32 v3, v3, s4
	v_and_b32_e32 v11, 32, v4
	v_and_b32_e32 v1, 0xfffffc00, v1
	s_sub_i32 s12, s12, s13
	v_or_b32_e32 v3, v3, v11
	v_sub_u32_e32 v0, v0, v1
	s_bfe_i32 s13, s12, 0x80000
	v_add_lshl_u32 v144, v3, v12, 1
	v_lshrrev_b32_e32 v1, 4, v0
	v_ashrrev_i32_e32 v3, 31, v8
	s_bfe_u32 s13, s13, 0x2000d
	v_bitop3_b32 v0, v1, v0, 32 bitop3:0x6c
	v_lshrrev_b32_e32 v3, 26, v3
	s_add_i32 s13, s12, s13
	v_ashrrev_i32_e32 v1, 31, v0
	v_add_u32_e32 v3, v8, v3
	s_bfe_i32 s15, s13, 0x80000
	s_and_b32 s13, s13, 0xfc
	v_lshrrev_b32_e32 v1, 26, v1
	v_ashrrev_i32_e32 v14, 6, v3
	s_sub_i32 s12, s12, s13
	v_add_u32_e32 v1, v0, v1
	v_lshlrev_b32_e32 v3, 3, v14
	s_lshl_b32 s14, s14, 2
	s_sext_i32_i16 s15, s15
	s_sext_i32_i8 s12, s12
	v_ashrrev_i32_e32 v13, 6, v1
	v_and_b32_e32 v3, 0x7ffff0, v3
	v_and_b32_e32 v1, 0xc0, v1
	s_add_i32 s52, s14, s12
	s_ashr_i32 s12, s15, 2
	v_add_u32_e32 v3, v13, v3
	v_lshlrev_b32_e32 v4, 5, v14
	v_sub_u32_e32 v0, v0, v1
	s_lshr_b32 s16, s15, 2
	s_mul_hi_i32 s13, s12, 0x2c0000
	s_mul_i32 s12, s12, 0x2c0000
	v_mul_lo_u32 v3, v3, s4
	v_and_b32_e32 v15, 32, v4
	v_ashrrev_i16_sdwa v0, v2, sext(v0) dst_sel:DWORD dst_unused:UNUSED_PAD src0_sel:DWORD src1_sel:BYTE_0
	s_add_u32 s28, s2, s12
	v_or_b32_e32 v3, v3, v15
	v_bfe_i32 v16, v0, 0, 16
	s_addc_u32 s29, s3, s13
	s_add_i32 s36, s33, 0
	v_add_lshl_u32 v146, v3, v16, 1
	s_add_i32 m0, s36, 0x10000
	s_mul_i32 s17, s52, 0x2c0000
	global_load_lds_dwordx4 v146, s[28:29]
	s_add_i32 m0, s36, 0x12000
	s_add_u32 s12, s28, 0x160000
	global_load_lds_dwordx4 v144, s[28:29]
	s_addc_u32 s13, s29, 0
	s_add_i32 m0, s36, 0x14000
	s_mul_hi_i32 s14, s52, 0x2c0000
	global_load_lds_dwordx4 v146, s[12:13]
	s_add_i32 m0, s36, 0x16000
	s_add_u32 s26, s0, s17
	s_addc_u32 s27, s1, s14
	s_add_i32 s37, s36, 0x2000
	global_load_lds_dwordx4 v144, s[12:13]
	s_mov_b32 m0, s36
	s_add_u32 s12, s26, 0x160000
	global_load_lds_dwordx4 v146, s[26:27]
	s_mov_b32 m0, s37
	s_addc_u32 s13, s27, 0
	s_add_i32 s38, s36, 0x4000
	global_load_lds_dwordx4 v144, s[26:27]
	s_mov_b32 m0, s38
	s_add_i32 s39, s36, 0x6000
	global_load_lds_dwordx4 v146, s[12:13]
	s_mov_b32 m0, s39
	v_mov_b32_e32 v147, 0
	global_load_lds_dwordx4 v144, s[12:13]
	v_mov_b32_e32 v145, v147
	s_cmp_eq_u32 s5, 1
	s_mov_b32 s40, 0
	v_lshl_add_u64 v[6:7], s[28:29], 0, v[146:147]
	v_lshl_add_u64 v[4:5], s[28:29], 0, v[144:145]
	s_mov_b64 s[12:13], 0x160000
	s_mov_b32 s18, 0x16000
	v_lshl_add_u64 v[0:1], s[26:27], 0, v[146:147]
	s_cselect_b64 s[14:15], -1, 0
	s_cmp_lg_u32 s5, 1
	v_lshl_add_u64 v[2:3], s[26:27], 0, v[144:145]
	s_cbranch_scc1 .LBB0_880
	s_barrier

;     __device__ __forceinline__ void operator()(const f32x4 (&acc)[2][2][4][2], const Unit& u, int wr, int wc, int fr, int fq) const {
;         const int row0 = u.pm * BM + wr * 64 + fr, col0 = u.pn * BM + wc * 32 + 4 * fq;
;         const float* gb = gate + (size_t)(u.pm >> 3) * NIN;
;         f32x4 gv[2][2];
; #pragma unroll
;         for (int bj = 0; bj < 2; ++bj)
; #pragma unroll
;             for (int n = 0; n < 2; ++n) gv[bj][n] = *(const f32x4*)(gb + col0 + bj * HALF + n * 16);
; #pragma unroll
;         for (int ai = 0; ai < 2; ++ai)
; #pragma unroll
;             for (int m = 0; m < 4; ++m) { const size_t off = (size_t)(row0 + ai * HALF + m * 16) * 2048 + col0;
; #pragma unroll
;                 for (int bj = 0; bj < 2; ++bj)
; #pragma unroll
;                     for (int n = 0; n < 2; ++n) { const f32x4 bs = *(const f32x4*)(base + off + bj * HALF + n * 16);
;                         *(f32x4*)(out + off + bj * HALF + n * 16) = bs + gv[bj][n] * acc[ai][bj][m][n]; } }
.LBB0_897:
	s_ashr_i32 s26, s52, 3
	v_lshl_add_u32 v160, s52, 8, v169
	v_lshl_or_b32 v64, s53, 8, v171
	s_mul_hi_i32 s27, s26, 0xc000
	s_mul_i32 s26, s26, 0xc000
	s_add_u32 s26, s41, s26
	v_ashrrev_i32_e32 v65, 31, v64
	s_addc_u32 s27, s42, s27
	v_lshlrev_b64 v[158:159], 2, v[64:65]
	v_lshlrev_b32_e32 v192, 13, v160
	v_lshl_add_u64 v[64:65], s[26:27], 0, v[158:159]
	v_add_u32_e32 v192, v192, v158
	global_load_dwordx4 v[128:131], v[64:65], off
	global_load_dwordx4 v[116:119], v[64:65], off offset:64
	global_load_dwordx4 v[108:111], v[64:65], off offset:512
	s_nop 0
	global_load_dwordx4 v[64:67], v[64:65], off offset:576
	s_mov_b64 s[26:27], -1
	v_add_u32_e32 v193, 0x20000, v192
	v_add_u32_e32 v224, 0x40000, v192
	v_add_u32_e32 v225, 0x60000, v192
	v_add_u32_e32 v226, 0x100000, v192
	v_add_u32_e32 v227, 0x120000, v192
	v_add_u32_e32 v228, 0x140000, v192
	v_add_u32_e32 v229, 0x160000, v192
	global_load_dwordx4 v[156:159], v192, s[8:9]
	global_load_dwordx4 v[176:179], v192, s[8:9] offset:64
	global_load_dwordx4 v[180:183], v192, s[8:9] offset:512
	global_load_dwordx4 v[184:187], v192, s[8:9] offset:576
	global_load_dwordx4 v[188:191], v193, s[8:9]
	global_load_dwordx4 v[196:199], v193, s[8:9] offset:64
	global_load_dwordx4 v[200:203], v193, s[8:9] offset:512
	global_load_dwordx4 v[204:207], v193, s[8:9] offset:576
	global_load_dwordx4 v[208:211], v224, s[8:9]
	global_load_dwordx4 v[212:215], v224, s[8:9] offset:64
	global_load_dwordx4 v[216:219], v224, s[8:9] offset:512
	global_load_dwordx4 v[220:223], v224, s[8:9] offset:576
	s_waitcnt vmcnt(11)
	v_pk_fma_f32 v[142:143], v[142:143], v[130:131], v[158:159]
	v_pk_fma_f32 v[140:141], v[140:141], v[128:129], v[156:157]
	global_store_dwordx4 v192, v[140:143], s[8:9]
	s_waitcnt vmcnt(11)
	v_pk_fma_f32 v[138:139], v[138:139], v[118:119], v[178:179]
	v_pk_fma_f32 v[136:137], v[136:137], v[116:117], v[176:177]
	global_store_dwordx4 v192, v[136:139], s[8:9] offset:64
	s_waitcnt vmcnt(11)
	v_pk_fma_f32 v[134:135], v[134:135], v[110:111], v[182:183]
	v_pk_fma_f32 v[132:133], v[132:133], v[108:109], v[180:181]
	global_store_dwordx4 v192, v[132:135], s[8:9] offset:512
	s_waitcnt vmcnt(11)
	v_pk_fma_f32 v[126:127], v[126:127], v[66:67], v[186:187]
	v_pk_fma_f32 v[124:125], v[124:125], v[64:65], v[184:185]
	global_store_dwordx4 v192, v[124:127], s[8:9] offset:576
	global_load_dwordx4 v[156:159], v225, s[8:9]
	global_load_dwordx4 v[176:179], v225, s[8:9] offset:64
	global_load_dwordx4 v[180:183], v225, s[8:9] offset:512
	global_load_dwordx4 v[184:187], v225, s[8:9] offset:576
	global_load_dwordx4 v[140:143], v226, s[8:9]
	global_load_dwordx4 v[136:139], v226, s[8:9] offset:64
	global_load_dwordx4 v[132:135], v226, s[8:9] offset:512
	global_load_dwordx4 v[124:127], v226, s[8:9] offset:576
	s_waitcnt vmcnt(19)
	v_pk_fma_f32 v[122:123], v[122:123], v[130:131], v[190:191]
	v_pk_fma_f32 v[120:121], v[120:121], v[128:129], v[188:189]
	global_store_dwordx4 v193, v[120:123], s[8:9]
	s_waitcnt vmcnt(19)
	v_pk_fma_f32 v[114:115], v[114:115], v[118:119], v[198:199]
	v_pk_fma_f32 v[112:113], v[112:113], v[116:117], v[196:197]
	global_store_dwordx4 v193, v[112:115], s[8:9] offset:64
	s_waitcnt vmcnt(19)
	v_pk_fma_f32 v[106:107], v[106:107], v[110:111], v[202:203]
	v_pk_fma_f32 v[104:105], v[104:105], v[108:109], v[200:201]
	global_store_dwordx4 v193, v[104:107], s[8:9] offset:512
	s_waitcnt vmcnt(19)
	v_pk_fma_f32 v[102:103], v[102:103], v[66:67], v[206:207]
	v_pk_fma_f32 v[100:101], v[100:101], v[64:65], v[204:205]
	global_store_dwordx4 v193, v[100:103], s[8:9] offset:576
	global_load_dwordx4 v[188:191], v227, s[8:9]
	global_load_dwordx4 v[196:199], v227, s[8:9] offset:64
	global_load_dwordx4 v[200:203], v227, s[8:9] offset:512
	global_load_dwordx4 v[204:207], v227, s[8:9] offset:576
	global_load_dwordx4 v[120:123], v228, s[8:9]
	global_load_dwordx4 v[112:115], v228, s[8:9] offset:64
	global_load_dwordx4 v[104:107], v228, s[8:9] offset:512
	global_load_dwordx4 v[100:103], v228, s[8:9] offset:576
	s_waitcnt vmcnt(27)
	v_pk_fma_f32 v[98:99], v[98:99], v[130:131], v[210:211]
	v_pk_fma_f32 v[96:97], v[96:97], v[128:129], v[208:209]
	global_store_dwordx4 v224, v[96:99], s[8:9]
	s_waitcnt vmcnt(27)
	v_pk_fma_f32 v[94:95], v[94:95], v[118:119], v[214:215]
	v_pk_fma_f32 v[92:93], v[92:93], v[116:117], v[212:213]
	global_store_dwordx4 v224, v[92:95], s[8:9] offset:64
	s_waitcnt vmcnt(27)
;     __device__ __forceinline__ void operator()(const f32x4 (&acc)[2][2][4][2], const Unit& u, int wr, int wc, int fr, int fq) const {
;     ...
;             for (int m = 0; m < 4; ++m) { const size_t off = (size_t)(row0 + ai * HALF + m * 16) * 2048 + col0;
; #pragma unroll
;                 for (int bj = 0; bj < 2; ++bj)
; #pragma unroll
;                     for (int n = 0; n < 2; ++n) { const f32x4 bs = *(const f32x4*)(base + off + bj * HALF + n * 16);
;                         *(f32x4*)(out + off + bj * HALF + n * 16) = bs + gv[bj][n] * acc[ai][bj][m][n]; } }
	v_pk_fma_f32 v[90:91], v[90:91], v[110:111], v[218:219]
	v_pk_fma_f32 v[88:89], v[88:89], v[108:109], v[216:217]
	global_store_dwordx4 v224, v[88:91], s[8:9] offset:512
	s_waitcnt vmcnt(27)
	v_pk_fma_f32 v[86:87], v[86:87], v[66:67], v[222:223]
	v_pk_fma_f32 v[84:85], v[84:85], v[64:65], v[220:221]
	global_store_dwordx4 v224, v[84:87], s[8:9] offset:576
	global_load_dwordx4 v[208:211], v229, s[8:9]
	global_load_dwordx4 v[212:215], v229, s[8:9] offset:64
	global_load_dwordx4 v[216:219], v229, s[8:9] offset:512
	global_load_dwordx4 v[220:223], v229, s[8:9] offset:576
	s_waitcnt vmcnt(27)
	v_pk_fma_f32 v[82:83], v[82:83], v[130:131], v[158:159]
	v_pk_fma_f32 v[80:81], v[80:81], v[128:129], v[156:157]
	global_store_dwordx4 v225, v[80:83], s[8:9]
	s_waitcnt vmcnt(27)
	v_pk_fma_f32 v[78:79], v[78:79], v[118:119], v[178:179]
	v_pk_fma_f32 v[76:77], v[76:77], v[116:117], v[176:177]
	global_store_dwordx4 v225, v[76:79], s[8:9] offset:64
	s_waitcnt vmcnt(27)
	v_pk_fma_f32 v[74:75], v[74:75], v[110:111], v[182:183]
	v_pk_fma_f32 v[72:73], v[72:73], v[108:109], v[180:181]
	global_store_dwordx4 v225, v[72:75], s[8:9] offset:512
	s_waitcnt vmcnt(27)
	v_pk_fma_f32 v[70:71], v[70:71], v[66:67], v[186:187]
	v_pk_fma_f32 v[68:69], v[68:69], v[64:65], v[184:185]
	global_store_dwordx4 v225, v[68:71], s[8:9] offset:576
	s_waitcnt vmcnt(27)
	v_pk_fma_f32 v[62:63], v[62:63], v[130:131], v[142:143]
	v_pk_fma_f32 v[60:61], v[60:61], v[128:129], v[140:141]
	global_store_dwordx4 v226, v[60:63], s[8:9]
	s_waitcnt vmcnt(27)
	v_pk_fma_f32 v[58:59], v[58:59], v[118:119], v[138:139]
	v_pk_fma_f32 v[56:57], v[56:57], v[116:117], v[136:137]
	global_store_dwordx4 v226, v[56:59], s[8:9] offset:64
	s_waitcnt vmcnt(27)
	v_pk_fma_f32 v[54:55], v[54:55], v[110:111], v[134:135]
	v_pk_fma_f32 v[52:53], v[52:53], v[108:109], v[132:133]
	global_store_dwordx4 v226, v[52:55], s[8:9] offset:512
	s_waitcnt vmcnt(27)
	v_pk_fma_f32 v[50:51], v[50:51], v[66:67], v[126:127]
	v_pk_fma_f32 v[48:49], v[48:49], v[64:65], v[124:125]
	global_store_dwordx4 v226, v[48:51], s[8:9] offset:576
	s_waitcnt vmcnt(23)
	v_pk_fma_f32 v[46:47], v[46:47], v[130:131], v[190:191]
	v_pk_fma_f32 v[44:45], v[44:45], v[128:129], v[188:189]
	global_store_dwordx4 v227, v[44:47], s[8:9]
	s_waitcnt vmcnt(23)
	v_pk_fma_f32 v[42:43], v[42:43], v[118:119], v[198:199]
	v_pk_fma_f32 v[40:41], v[40:41], v[116:117], v[196:197]
	global_store_dwordx4 v227, v[40:43], s[8:9] offset:64
	s_waitcnt vmcnt(23)
	v_pk_fma_f32 v[38:39], v[38:39], v[110:111], v[202:203]
	v_pk_fma_f32 v[36:37], v[36:37], v[108:109], v[200:201]
	global_store_dwordx4 v227, v[36:39], s[8:9] offset:512
	s_waitcnt vmcnt(23)
	v_pk_fma_f32 v[34:35], v[34:35], v[66:67], v[206:207]
	v_pk_fma_f32 v[32:33], v[32:33], v[64:65], v[204:205]
	global_store_dwordx4 v227, v[32:35], s[8:9] offset:576
	s_waitcnt vmcnt(23)
	v_pk_fma_f32 v[30:31], v[30:31], v[130:131], v[122:123]
	v_pk_fma_f32 v[28:29], v[28:29], v[128:129], v[120:121]
	global_store_dwordx4 v228, v[28:31], s[8:9]
	s_waitcnt vmcnt(23)
	v_pk_fma_f32 v[26:27], v[26:27], v[118:119], v[114:115]
	v_pk_fma_f32 v[24:25], v[24:25], v[116:117], v[112:113]
	global_store_dwordx4 v228, v[24:27], s[8:9] offset:64
	s_waitcnt vmcnt(23)
	v_pk_fma_f32 v[22:23], v[22:23], v[110:111], v[106:107]
	v_pk_fma_f32 v[20:21], v[20:21], v[108:109], v[104:105]
	global_store_dwordx4 v228, v[20:23], s[8:9] offset:512
	s_waitcnt vmcnt(23)
	v_pk_fma_f32 v[18:19], v[18:19], v[66:67], v[102:103]
	v_pk_fma_f32 v[16:17], v[16:17], v[64:65], v[100:101]
	global_store_dwordx4 v228, v[16:19], s[8:9] offset:576
	s_waitcnt vmcnt(19)
	v_pk_fma_f32 v[14:15], v[14:15], v[130:131], v[210:211]
	v_pk_fma_f32 v[12:13], v[12:13], v[128:129], v[208:209]
	global_store_dwordx4 v229, v[12:15], s[8:9]
	s_waitcnt vmcnt(19)
	v_pk_fma_f32 v[10:11], v[10:11], v[118:119], v[214:215]
	v_pk_fma_f32 v[8:9], v[8:9], v[116:117], v[212:213]
	global_store_dwordx4 v229, v[8:11], s[8:9] offset:64
	s_waitcnt vmcnt(19)
	v_pk_fma_f32 v[6:7], v[6:7], v[110:111], v[218:219]
	v_pk_fma_f32 v[4:5], v[4:5], v[108:109], v[216:217]
	global_store_dwordx4 v229, v[4:7], s[8:9] offset:512
	s_waitcnt vmcnt(19)
	v_pk_fma_f32 v[2:3], v[2:3], v[66:67], v[222:223]
	v_pk_fma_f32 v[0:1], v[0:1], v[64:65], v[220:221]
	global_store_dwordx4 v229, v[0:3], s[8:9] offset:576
	s_and_b64 vcc, exec, s[4:5]
	s_cbranch_vccnz .LBB0_882
	s_andn2_b64 vcc, exec, s[14:15]
	s_cbranch_vccnz .LBB0_881
	s_barrier
	s_branch .LBB0_881
